# attention: leading K-fragment read burst cut from 8 to 6 per half-step (the two last-consumed fragments are read behind MFMA10)
# speedup vs baseline: 1.0081x; 1.0081x over previous
.LBB0_895:
	ds_read_b128 v[124:127], v201 offset:12288
	ds_read_b128 v[128:131], v201 offset:13312
	ds_read_b128 v[136:139], v201 offset:15360
	ds_read_b128 v[148:151], v201 offset:18432
	ds_read_b128 v[152:155], v201 offset:19456
	ds_read_b128 v[204:207], v201 offset:21504
	s_waitcnt lgkmcnt(5)
	v_mfma_f32_16x16x32_bf16 v[132:135], v[124:127], v[12:15], v[44:47]
	v_exp_f32_e32 v195, v84
	v_exp_f32_e32 v194, v88
	v_mfma_f32_16x16x32_bf16 v[124:127], v[124:127], v[16:19], v[48:51]
	v_exp_f32_e32 v88, v91
	v_exp_f32_e32 v84, v81
	s_waitcnt lgkmcnt(2)
	v_mfma_f32_16x16x32_bf16 v[190:193], v[148:151], v[12:15], v[44:47]
	v_exp_f32_e32 v81, v78
	v_exp_f32_e32 v79, v79
	v_mfma_f32_16x16x32_bf16 v[148:151], v[148:151], v[16:19], v[48:51]
	v_exp_f32_e32 v78, v83
	v_exp_f32_e32 v61, v61
	v_mfma_f32_16x16x32_bf16 v[144:147], v[136:139], v[12:15], v[44:47]
	v_exp_f32_e32 v63, v63
	v_exp_f32_e32 v83, v64
	v_mfma_f32_16x16x32_bf16 v[136:139], v[136:139], v[16:19], v[48:51]
	v_exp_f32_e32 v64, v74
	v_exp_f32_e32 v67, v67
	s_waitcnt lgkmcnt(0)
	v_mfma_f32_16x16x32_bf16 v[212:215], v[204:207], v[12:15], v[44:47]
	v_exp_f32_e32 v250, v90
	v_mfma_f32_16x16x32_bf16 v[204:207], v[204:207], v[16:19], v[48:51]
	v_mfma_f32_16x16x32_bf16 v[132:135], v[128:131], v[4:7], v[132:135]
	v_mfma_f32_16x16x32_bf16 v[124:127], v[128:131], v[20:23], v[124:127]
	ds_read_b128 v[128:131], v201 offset:16384
	ds_read_b128 v[216:219], v201 offset:17408
	ds_read_b128 v[140:143], v201 offset:14336
	ds_read_b128 v[208:211], v201 offset:20480
	v_mfma_f32_16x16x32_bf16 v[220:223], v[152:155], v[20:23], v[148:151]
	v_exp_f32_e32 v249, v85
	v_exp_f32_e32 v248, v89
	v_exp_f32_e32 v251, v86
	ds_read_b128 v[148:151], v201 offset:22528
	ds_read_b128 v[224:227], v201 offset:23552
	s_waitcnt lgkmcnt(5)
	v_mfma_f32_16x16x32_bf16 v[144:147], v[128:131], v[4:7], v[144:147]
	v_exp_f32_e32 v89, v87
	v_exp_f32_e32 v87, v76
	v_mfma_f32_16x16x32_bf16 v[128:131], v[128:131], v[20:23], v[136:139]
	v_exp_f32_e32 v86, v80
	s_waitcnt lgkmcnt(1)
	v_mfma_f32_16x16x32_bf16 v[204:207], v[148:151], v[20:23], v[204:207]
	v_exp_f32_e32 v85, v77
	v_exp_f32_e32 v80, v82
	v_mfma_f32_16x16x32_bf16 v[136:139], v[152:155], v[4:7], v[190:193]
	v_exp_f32_e32 v77, v60
	v_mfma_f32_16x16x32_bf16 v[212:215], v[148:151], v[4:7], v[212:215]
	v_exp_f32_e32 v76, v68
	v_exp_f32_e32 v60, v69
	v_mfma_f32_16x16x32_bf16 v[148:151], v[140:143], v[8:11], v[132:135]
	v_exp_f32_e32 v69, v62
	v_mfma_f32_16x16x32_bf16 v[152:155], v[140:143], v[24:27], v[124:127]
	v_exp_f32_e32 v68, v70
	v_exp_f32_e32 v62, v71
	v_mfma_f32_16x16x32_bf16 v[140:143], v[216:219], v[8:11], v[144:147]
	v_exp_f32_e32 v82, v72
	v_mfma_f32_16x16x32_bf16 v[144:147], v[216:219], v[24:27], v[128:131]
	v_exp_f32_e32 v71, v65
	v_exp_f32_e32 v70, v73
	s_waitcnt lgkmcnt(0)
	v_mfma_f32_16x16x32_bf16 v[128:131], v[224:227], v[24:27], v[204:207]
	v_exp_f32_e32 v65, v66
	ds_read_b128 v[204:207], v200 offset:24576
	v_mfma_f32_16x16x32_bf16 v[132:135], v[208:211], v[8:11], v[136:139]
	v_exp_f32_e32 v66, v75
	v_cvt_pk_bf16_f32 v90, v77, v61
	v_mfma_f32_16x16x32_bf16 v[136:139], v[208:211], v[24:27], v[220:223]
	v_cvt_pk_bf16_f32 v208, v195, v249
	v_cvt_pk_bf16_f32 v209, v251, v89
	v_cvt_pk_bf16_f32 v210, v87, v85
	v_mfma_f32_16x16x32_bf16 v[124:127], v[224:227], v[8:11], v[212:215]
	v_cvt_pk_bf16_f32 v211, v81, v79
	ds_read_b128 v[216:219], v200 offset:26624
	ds_read_b128 v[220:223], v200 offset:25600
	v_cvt_pk_bf16_f32 v212, v194, v248
	v_cvt_pk_bf16_f32 v213, v250, v88
	v_cvt_pk_bf16_f32 v214, v86, v84
	v_cvt_pk_bf16_f32 v215, v80, v78
	s_waitcnt lgkmcnt(2)
	v_mfma_f32_16x16x32_bf16 v[120:123], v[204:207], v[208:211], v[120:123]
	v_cvt_pk_bf16_f32 v91, v69, v63
	v_mfma_f32_16x16x32_bf16 v[104:107], v[204:207], v[212:215], v[104:107]
	ds_read_b128 v[204:207], v200 offset:28672
	ds_read_b128 v[224:227], v200 offset:27648
	s_waitcnt lgkmcnt(3)
	v_mfma_f32_16x16x32_bf16 v[228:231], v[216:219], v[208:211], v[116:119]
	v_mfma_f32_16x16x32_bf16 v[100:103], v[216:219], v[212:215], v[100:103]
	s_nop 1
	ds_read_b128 v[116:119], v200 offset:30720
	ds_read_b128 v[216:219], v200 offset:29696
	s_waitcnt lgkmcnt(3)
	v_mfma_f32_16x16x32_bf16 v[232:235], v[204:207], v[208:211], v[112:115]
	v_mfma_f32_16x16x32_bf16 v[96:99], v[204:207], v[212:215], v[96:99]
	ds_read_b128 v[204:207], v200 offset:31744
	s_waitcnt lgkmcnt(2)
	v_mfma_f32_16x16x32_bf16 v[208:211], v[116:119], v[208:211], v[108:111]
	v_mfma_f32_16x16x32_bf16 v[72:75], v[116:119], v[212:215], v[92:95]
	v_cvt_pk_bf16_f32 v212, v76, v60
	v_cvt_pk_bf16_f32 v213, v68, v62
	v_cvt_pk_bf16_f32 v214, v82, v70
	v_cvt_pk_bf16_f32 v92, v83, v71
	v_cvt_pk_bf16_f32 v93, v65, v67
	v_cvt_pk_bf16_f32 v215, v64, v66
	s_nop 0
	v_mfma_f32_16x16x32_bf16 v[120:123], v[220:223], v[90:93], v[120:123]
	v_mfma_f32_16x16x32_bf16 v[116:119], v[220:223], v[212:215], v[104:107]
	v_max3_f32 v244, v152, v153, v154
	v_max3_f32 v245, v148, v149, v150
	v_mfma_f32_16x16x32_bf16 v[112:115], v[224:227], v[90:93], v[228:231]
	v_max3_f32 v244, v244, v155, v144
	v_max3_f32 v245, v245, v151, v140
	v_mfma_f32_16x16x32_bf16 v[108:111], v[224:227], v[212:215], v[100:103]
	v_max3_f32 v244, v244, v145, v146
	v_max3_f32 v245, v245, v141, v142
	s_waitcnt lgkmcnt(1)
	v_mfma_f32_16x16x32_bf16 v[104:107], v[216:219], v[90:93], v[232:235]
	v_max3_f32 v244, v244, v147, v136
	v_max3_f32 v245, v245, v143, v132
	v_mfma_f32_16x16x32_bf16 v[100:103], v[216:219], v[212:215], v[96:99]
	v_max3_f32 v244, v244, v137, v138
	v_max3_f32 v245, v245, v133, v134
	s_waitcnt lgkmcnt(0)
	v_mfma_f32_16x16x32_bf16 v[92:95], v[204:207], v[90:93], v[208:211]
	v_max3_f32 v244, v244, v139, v128
	v_max3_f32 v245, v245, v135, v124
	v_mfma_f32_16x16x32_bf16 v[96:99], v[204:207], v[212:215], v[72:75]
	v_max3_f32 v244, v244, v129, v130
	v_max3_f32 v245, v245, v125, v126
	s_waitcnt vmcnt(0)
	ds_write_b128 v197, v[32:35] offset:53248
	s_and_saveexec_b64 s[16:17], s[10:11]
	ds_write_b128 v199, v[36:39] offset:53248
	s_or_b64 exec, exec, s[16:17]

.LBB0_907:
	ds_read_b128 v[60:63], v201 offset:40960
	ds_read_b128 v[64:67], v201 offset:41984
	ds_read_b128 v[72:75], v201 offset:44032
	ds_read_b128 v[84:87], v201 offset:47104
	ds_read_b128 v[88:91], v201 offset:48128
	ds_read_b128 v[190:193], v201 offset:50176
	s_waitcnt lgkmcnt(5)
	v_mfma_f32_16x16x32_bf16 v[68:71], v[60:63], v[12:15], v[44:47]
	v_exp_f32_e32 v149, v149
	v_exp_f32_e32 v151, v151
	v_mfma_f32_16x16x32_bf16 v[60:63], v[60:63], v[16:19], v[48:51]
	v_exp_f32_e32 v143, v143
	v_exp_f32_e32 v133, v133
	s_waitcnt lgkmcnt(2)
	v_mfma_f32_16x16x32_bf16 v[186:189], v[84:87], v[12:15], v[44:47]
	v_exp_f32_e32 v135, v135
	v_exp_f32_e32 v127, v127
	v_mfma_f32_16x16x32_bf16 v[84:87], v[84:87], v[16:19], v[48:51]
	v_exp_f32_e32 v249, v148
	v_exp_f32_e32 v248, v152
	v_mfma_f32_16x16x32_bf16 v[80:83], v[72:75], v[12:15], v[44:47]
	v_exp_f32_e32 v148, v153
	v_mfma_f32_16x16x32_bf16 v[72:75], v[72:75], v[16:19], v[48:51]
	v_exp_f32_e32 v153, v150
	v_exp_f32_e32 v152, v154
	s_waitcnt lgkmcnt(0)
	v_mfma_f32_16x16x32_bf16 v[208:211], v[190:193], v[12:15], v[44:47]
	v_exp_f32_e32 v150, v155
	v_mfma_f32_16x16x32_bf16 v[190:193], v[190:193], v[16:19], v[48:51]
	v_exp_f32_e32 v155, v141
	v_exp_f32_e32 v154, v145
	v_mfma_f32_16x16x32_bf16 v[68:71], v[64:67], v[4:7], v[68:71]
	v_exp_f32_e32 v145, v142
	v_mfma_f32_16x16x32_bf16 v[60:63], v[64:67], v[20:23], v[60:63]
	v_exp_f32_e32 v142, v147
	ds_read_b128 v[64:67], v201 offset:45056
	ds_read_b128 v[212:215], v201 offset:46080
	ds_read_b128 v[76:79], v201 offset:43008
	ds_read_b128 v[204:207], v201 offset:49152
	v_mfma_f32_16x16x32_bf16 v[216:219], v[88:91], v[20:23], v[84:87]
	v_exp_f32_e32 v141, v132
	v_exp_f32_e32 v132, v137
	v_exp_f32_e32 v251, v140
	ds_read_b128 v[84:87], v201 offset:51200
	ds_read_b128 v[220:223], v201 offset:52224
	s_waitcnt lgkmcnt(5)
	v_mfma_f32_16x16x32_bf16 v[80:83], v[64:67], v[4:7], v[80:83]
	v_exp_f32_e32 v250, v144
	v_mfma_f32_16x16x32_bf16 v[64:67], v[64:67], v[20:23], v[72:75]
	v_exp_f32_e32 v144, v146
	v_exp_f32_e32 v140, v136
	v_mfma_f32_16x16x32_bf16 v[72:75], v[88:91], v[4:7], v[186:189]
	v_exp_f32_e32 v137, v134
	s_waitcnt lgkmcnt(1)
	v_mfma_f32_16x16x32_bf16 v[188:191], v[84:87], v[20:23], v[190:193]
	v_exp_f32_e32 v136, v138
	v_exp_f32_e32 v134, v139
	v_mfma_f32_16x16x32_bf16 v[88:91], v[76:79], v[24:27], v[60:63]
	v_exp_f32_e32 v139, v124
	v_mfma_f32_16x16x32_bf16 v[60:63], v[204:207], v[8:11], v[72:75]
	v_exp_f32_e32 v138, v128
	s_waitcnt lgkmcnt(0)
	v_mfma_f32_16x16x32_bf16 v[72:75], v[220:223], v[24:27], v[188:191]
	v_exp_f32_e32 v147, v125
	ds_read_b128 v[190:193], v203 offset:16384
	v_mfma_f32_16x16x32_bf16 v[208:211], v[84:87], v[4:7], v[208:211]
	v_exp_f32_e32 v146, v129
	v_mfma_f32_16x16x32_bf16 v[84:87], v[76:79], v[8:11], v[68:71]
	v_exp_f32_e32 v125, v126
	v_mfma_f32_16x16x32_bf16 v[76:79], v[212:215], v[8:11], v[80:83]
	v_exp_f32_e32 v124, v130
	v_mfma_f32_16x16x32_bf16 v[80:83], v[212:215], v[24:27], v[64:67]
	v_exp_f32_e32 v126, v131
	v_mfma_f32_16x16x32_bf16 v[68:71], v[204:207], v[24:27], v[216:219]
	ds_read_b128 v[212:215], v203 offset:18432
	s_nop 1
	ds_read_b128 v[216:219], v203 offset:17408
	v_cvt_pk_bf16_f32 v204, v249, v149
	v_cvt_pk_bf16_f32 v205, v153, v151
	v_mfma_f32_16x16x32_bf16 v[64:67], v[220:223], v[8:11], v[208:211]
	v_cvt_pk_bf16_f32 v206, v251, v155
	v_cvt_pk_bf16_f32 v207, v145, v143
	v_cvt_pk_bf16_f32 v208, v248, v148
	v_cvt_pk_bf16_f32 v209, v152, v150
	v_cvt_pk_bf16_f32 v210, v250, v154
	v_cvt_pk_bf16_f32 v211, v144, v142
	s_waitcnt lgkmcnt(2)
	v_mfma_f32_16x16x32_bf16 v[120:123], v[190:193], v[204:207], v[120:123]
	v_mfma_f32_16x16x32_bf16 v[116:119], v[190:193], v[208:211], v[116:119]
	ds_read_b128 v[190:193], v203 offset:20480
	ds_read_b128 v[220:223], v203 offset:19456
	s_waitcnt lgkmcnt(3)
	v_mfma_f32_16x16x32_bf16 v[112:115], v[212:215], v[204:207], v[112:115]
	v_mfma_f32_16x16x32_bf16 v[108:111], v[212:215], v[208:211], v[108:111]
	ds_read_b128 v[212:215], v203 offset:22528
	ds_read_b128 v[224:227], v203 offset:21504
	ds_read_b128 v[232:235], v203 offset:23552
	s_waitcnt lgkmcnt(4)
	v_mfma_f32_16x16x32_bf16 v[228:231], v[190:193], v[204:207], v[104:107]
	v_mfma_f32_16x16x32_bf16 v[190:193], v[190:193], v[208:211], v[100:103]
	s_waitcnt lgkmcnt(2)
	v_mfma_f32_16x16x32_bf16 v[92:95], v[212:215], v[204:207], v[92:95]
	v_cvt_pk_bf16_f32 v204, v141, v133
	v_cvt_pk_bf16_f32 v205, v137, v135
	v_cvt_pk_bf16_f32 v206, v139, v147
	v_mfma_f32_16x16x32_bf16 v[128:131], v[212:215], v[208:211], v[96:99]
	v_cvt_pk_bf16_f32 v207, v125, v127
	v_cvt_pk_bf16_f32 v208, v140, v132
	v_cvt_pk_bf16_f32 v209, v136, v134
	v_cvt_pk_bf16_f32 v210, v138, v146
	v_cvt_pk_bf16_f32 v211, v124, v126
	v_mfma_f32_16x16x32_bf16 v[120:123], v[216:219], v[204:207], v[120:123]
	s_nop 0
	v_mfma_f32_16x16x32_bf16 v[104:107], v[216:219], v[208:211], v[116:119]
	v_max3_f32 v246, v88, v89, v90
	v_max3_f32 v247, v84, v85, v86
	v_mfma_f32_16x16x32_bf16 v[116:119], v[220:223], v[204:207], v[112:115]
	v_max3_f32 v246, v246, v91, v80
	v_max3_f32 v247, v247, v87, v76
	v_mfma_f32_16x16x32_bf16 v[100:103], v[220:223], v[208:211], v[108:111]
	v_max3_f32 v246, v246, v81, v82
	v_max3_f32 v247, v247, v77, v78
	s_waitcnt lgkmcnt(1)
	v_mfma_f32_16x16x32_bf16 v[112:115], v[224:227], v[204:207], v[228:231]
	v_max3_f32 v246, v246, v83, v68
	v_max3_f32 v247, v247, v79, v60
	v_mfma_f32_16x16x32_bf16 v[96:99], v[224:227], v[208:211], v[190:193]
	v_max3_f32 v246, v246, v69, v70
	v_max3_f32 v247, v247, v61, v62
	s_waitcnt lgkmcnt(0)
	v_mfma_f32_16x16x32_bf16 v[108:111], v[232:235], v[204:207], v[92:95]
	v_max3_f32 v246, v246, v71, v72
	v_max3_f32 v247, v247, v63, v64
	v_mfma_f32_16x16x32_bf16 v[92:95], v[232:235], v[208:211], v[128:131]
	v_max3_f32 v246, v246, v73, v74
	v_max3_f32 v247, v247, v65, v66
	s_waitcnt vmcnt(0)
	ds_write_b128 v197, v[52:55]
	s_and_saveexec_b64 s[16:17], s[10:11]
	ds_write_b128 v199, v[28:31]
	s_or_b64 exec, exec, s[16:17]

.Lattn2_895:
	ds_read_b128 v[124:127], v201 offset:53248
	ds_read_b128 v[128:131], v201 offset:54272
	ds_read_b128 v[136:139], v201 offset:56320
	ds_read_b128 v[148:151], v201 offset:59392
	ds_read_b128 v[152:155], v201 offset:60416
	ds_read_b128 v[204:207], v201 offset:62464
	s_waitcnt lgkmcnt(5)
	v_mfma_f32_16x16x32_bf16 v[132:135], v[124:127], v[12:15], v[44:47]
	v_exp_f32_e32 v195, v84
	v_exp_f32_e32 v194, v88
	v_mfma_f32_16x16x32_bf16 v[124:127], v[124:127], v[16:19], v[48:51]
	v_exp_f32_e32 v88, v91
	v_exp_f32_e32 v84, v81
	s_waitcnt lgkmcnt(2)
	v_mfma_f32_16x16x32_bf16 v[190:193], v[148:151], v[12:15], v[44:47]
	v_exp_f32_e32 v81, v78
	v_exp_f32_e32 v79, v79
	v_mfma_f32_16x16x32_bf16 v[148:151], v[148:151], v[16:19], v[48:51]
	v_exp_f32_e32 v78, v83
	v_exp_f32_e32 v61, v61
	v_mfma_f32_16x16x32_bf16 v[144:147], v[136:139], v[12:15], v[44:47]
	v_exp_f32_e32 v63, v63
	v_exp_f32_e32 v83, v64
	v_mfma_f32_16x16x32_bf16 v[136:139], v[136:139], v[16:19], v[48:51]
	v_exp_f32_e32 v64, v74
	v_exp_f32_e32 v67, v67
	s_waitcnt lgkmcnt(0)
	v_mfma_f32_16x16x32_bf16 v[212:215], v[204:207], v[12:15], v[44:47]
	v_exp_f32_e32 v250, v90
	v_mfma_f32_16x16x32_bf16 v[204:207], v[204:207], v[16:19], v[48:51]
	v_mfma_f32_16x16x32_bf16 v[132:135], v[128:131], v[4:7], v[132:135]
	v_mfma_f32_16x16x32_bf16 v[124:127], v[128:131], v[20:23], v[124:127]
	ds_read_b128 v[128:131], v201 offset:57344
	ds_read_b128 v[216:219], v201 offset:58368
	ds_read_b128 v[140:143], v201 offset:55296
	ds_read_b128 v[208:211], v201 offset:61440
	v_mfma_f32_16x16x32_bf16 v[220:223], v[152:155], v[20:23], v[148:151]
	v_exp_f32_e32 v249, v85
	v_exp_f32_e32 v248, v89
	v_exp_f32_e32 v251, v86
	ds_read_b128 v[148:151], v201 offset:63488
	ds_read_b128 v[224:227], v201 offset:64512
	s_waitcnt lgkmcnt(5)
	v_mfma_f32_16x16x32_bf16 v[144:147], v[128:131], v[4:7], v[144:147]
	v_exp_f32_e32 v89, v87
	v_exp_f32_e32 v87, v76
	v_mfma_f32_16x16x32_bf16 v[128:131], v[128:131], v[20:23], v[136:139]
	v_exp_f32_e32 v86, v80
	s_waitcnt lgkmcnt(1)
	v_mfma_f32_16x16x32_bf16 v[204:207], v[148:151], v[20:23], v[204:207]
	v_exp_f32_e32 v85, v77
	v_exp_f32_e32 v80, v82
	v_mfma_f32_16x16x32_bf16 v[136:139], v[152:155], v[4:7], v[190:193]
	v_exp_f32_e32 v77, v60
	v_mfma_f32_16x16x32_bf16 v[212:215], v[148:151], v[4:7], v[212:215]
	v_exp_f32_e32 v76, v68
	v_exp_f32_e32 v60, v69
	v_mfma_f32_16x16x32_bf16 v[148:151], v[140:143], v[8:11], v[132:135]
	v_exp_f32_e32 v69, v62
	v_mfma_f32_16x16x32_bf16 v[152:155], v[140:143], v[24:27], v[124:127]
	v_exp_f32_e32 v68, v70
	v_exp_f32_e32 v62, v71
	v_mfma_f32_16x16x32_bf16 v[140:143], v[216:219], v[8:11], v[144:147]
	v_exp_f32_e32 v82, v72
	v_mfma_f32_16x16x32_bf16 v[144:147], v[216:219], v[24:27], v[128:131]
	v_exp_f32_e32 v71, v65
	v_exp_f32_e32 v70, v73
	s_waitcnt lgkmcnt(0)
	v_mfma_f32_16x16x32_bf16 v[128:131], v[224:227], v[24:27], v[204:207]
	v_exp_f32_e32 v65, v66
	ds_read_b128 v[204:207], v203 offset:24576
	v_mfma_f32_16x16x32_bf16 v[132:135], v[208:211], v[8:11], v[136:139]
	v_exp_f32_e32 v66, v75
	v_cvt_pk_bf16_f32 v90, v77, v61
	v_mfma_f32_16x16x32_bf16 v[136:139], v[208:211], v[24:27], v[220:223]
	v_cvt_pk_bf16_f32 v208, v195, v249
	v_cvt_pk_bf16_f32 v209, v251, v89
	v_cvt_pk_bf16_f32 v210, v87, v85
	v_mfma_f32_16x16x32_bf16 v[124:127], v[224:227], v[8:11], v[212:215]
	v_cvt_pk_bf16_f32 v211, v81, v79
	ds_read_b128 v[216:219], v203 offset:26624
	ds_read_b128 v[220:223], v203 offset:25600
	v_cvt_pk_bf16_f32 v212, v194, v248
	v_cvt_pk_bf16_f32 v213, v250, v88
	v_cvt_pk_bf16_f32 v214, v86, v84
	v_cvt_pk_bf16_f32 v215, v80, v78
	s_waitcnt lgkmcnt(2)
	v_mfma_f32_16x16x32_bf16 v[120:123], v[204:207], v[208:211], v[120:123]
	v_cvt_pk_bf16_f32 v91, v69, v63
	v_mfma_f32_16x16x32_bf16 v[104:107], v[204:207], v[212:215], v[104:107]
	ds_read_b128 v[204:207], v203 offset:28672
	ds_read_b128 v[224:227], v203 offset:27648
	s_waitcnt lgkmcnt(3)
	v_mfma_f32_16x16x32_bf16 v[228:231], v[216:219], v[208:211], v[116:119]
	v_mfma_f32_16x16x32_bf16 v[100:103], v[216:219], v[212:215], v[100:103]
	s_nop 1
	ds_read_b128 v[116:119], v203 offset:30720
	ds_read_b128 v[216:219], v203 offset:29696
	s_waitcnt lgkmcnt(3)
	v_mfma_f32_16x16x32_bf16 v[232:235], v[204:207], v[208:211], v[112:115]
	v_mfma_f32_16x16x32_bf16 v[96:99], v[204:207], v[212:215], v[96:99]
	ds_read_b128 v[204:207], v203 offset:31744
	s_waitcnt lgkmcnt(2)
	v_mfma_f32_16x16x32_bf16 v[208:211], v[116:119], v[208:211], v[108:111]
	v_mfma_f32_16x16x32_bf16 v[72:75], v[116:119], v[212:215], v[92:95]
	v_cvt_pk_bf16_f32 v212, v76, v60
	v_cvt_pk_bf16_f32 v213, v68, v62
	v_cvt_pk_bf16_f32 v214, v82, v70
	v_cvt_pk_bf16_f32 v92, v83, v71
	v_cvt_pk_bf16_f32 v93, v65, v67
	v_cvt_pk_bf16_f32 v215, v64, v66
	s_nop 0
	v_mfma_f32_16x16x32_bf16 v[120:123], v[220:223], v[90:93], v[120:123]
	v_mfma_f32_16x16x32_bf16 v[116:119], v[220:223], v[212:215], v[104:107]
	v_max3_f32 v244, v152, v153, v154
	v_max3_f32 v245, v148, v149, v150
	v_mfma_f32_16x16x32_bf16 v[112:115], v[224:227], v[90:93], v[228:231]
	v_max3_f32 v244, v244, v155, v144
	v_max3_f32 v245, v245, v151, v140
	v_mfma_f32_16x16x32_bf16 v[108:111], v[224:227], v[212:215], v[100:103]
	v_max3_f32 v244, v244, v145, v146
	v_max3_f32 v245, v245, v141, v142
	s_waitcnt lgkmcnt(1)
	v_mfma_f32_16x16x32_bf16 v[104:107], v[216:219], v[90:93], v[232:235]
	v_max3_f32 v244, v244, v147, v136
	v_max3_f32 v245, v245, v143, v132
	v_mfma_f32_16x16x32_bf16 v[100:103], v[216:219], v[212:215], v[96:99]
	v_max3_f32 v244, v244, v137, v138
	v_max3_f32 v245, v245, v133, v134
	s_waitcnt lgkmcnt(0)
	v_mfma_f32_16x16x32_bf16 v[92:95], v[204:207], v[90:93], v[208:211]
	v_max3_f32 v244, v244, v139, v128
	v_max3_f32 v245, v245, v135, v124
	v_mfma_f32_16x16x32_bf16 v[96:99], v[204:207], v[212:215], v[72:75]
	v_max3_f32 v244, v244, v129, v130
	v_max3_f32 v245, v245, v125, v126
	s_waitcnt vmcnt(0)
	ds_write_b128 v197, v[32:35] offset:12288
	s_and_saveexec_b64 s[16:17], s[10:11]
	ds_write_b128 v199, v[36:39] offset:12288
	s_or_b64 exec, exec, s[16:17]

.Lattn2_907:
	ds_read_b128 v[60:63], v201
	ds_read_b128 v[64:67], v201 offset:1024
	ds_read_b128 v[72:75], v201 offset:3072
	ds_read_b128 v[84:87], v201 offset:6144
	ds_read_b128 v[88:91], v201 offset:7168
	ds_read_b128 v[190:193], v201 offset:9216
	s_waitcnt lgkmcnt(5)
	v_mfma_f32_16x16x32_bf16 v[68:71], v[60:63], v[12:15], v[44:47]
	v_exp_f32_e32 v149, v149
	v_exp_f32_e32 v151, v151
	v_mfma_f32_16x16x32_bf16 v[60:63], v[60:63], v[16:19], v[48:51]
	v_exp_f32_e32 v143, v143
	v_exp_f32_e32 v133, v133
	s_waitcnt lgkmcnt(2)
	v_mfma_f32_16x16x32_bf16 v[186:189], v[84:87], v[12:15], v[44:47]
	v_exp_f32_e32 v135, v135
	v_exp_f32_e32 v127, v127
	v_mfma_f32_16x16x32_bf16 v[84:87], v[84:87], v[16:19], v[48:51]
	v_exp_f32_e32 v249, v148
	v_exp_f32_e32 v248, v152
	v_mfma_f32_16x16x32_bf16 v[80:83], v[72:75], v[12:15], v[44:47]
	v_exp_f32_e32 v148, v153
	v_mfma_f32_16x16x32_bf16 v[72:75], v[72:75], v[16:19], v[48:51]
	v_exp_f32_e32 v153, v150
	v_exp_f32_e32 v152, v154
	s_waitcnt lgkmcnt(0)
	v_mfma_f32_16x16x32_bf16 v[208:211], v[190:193], v[12:15], v[44:47]
	v_exp_f32_e32 v150, v155
	v_mfma_f32_16x16x32_bf16 v[190:193], v[190:193], v[16:19], v[48:51]
	v_exp_f32_e32 v155, v141
	v_exp_f32_e32 v154, v145
	v_mfma_f32_16x16x32_bf16 v[68:71], v[64:67], v[4:7], v[68:71]
	v_exp_f32_e32 v145, v142
	v_mfma_f32_16x16x32_bf16 v[60:63], v[64:67], v[20:23], v[60:63]
	v_exp_f32_e32 v142, v147
	ds_read_b128 v[64:67], v201 offset:4096
	ds_read_b128 v[212:215], v201 offset:5120
	ds_read_b128 v[76:79], v201 offset:2048
	ds_read_b128 v[204:207], v201 offset:8192
	v_mfma_f32_16x16x32_bf16 v[216:219], v[88:91], v[20:23], v[84:87]
	v_exp_f32_e32 v141, v132
	v_exp_f32_e32 v132, v137
	v_exp_f32_e32 v251, v140
	ds_read_b128 v[84:87], v201 offset:10240
	ds_read_b128 v[220:223], v201 offset:11264
	s_waitcnt lgkmcnt(5)
	v_mfma_f32_16x16x32_bf16 v[80:83], v[64:67], v[4:7], v[80:83]
	v_exp_f32_e32 v250, v144
	v_mfma_f32_16x16x32_bf16 v[64:67], v[64:67], v[20:23], v[72:75]
	v_exp_f32_e32 v144, v146
	v_exp_f32_e32 v140, v136
	v_mfma_f32_16x16x32_bf16 v[72:75], v[88:91], v[4:7], v[186:189]
	v_exp_f32_e32 v137, v134
	s_waitcnt lgkmcnt(1)
	v_mfma_f32_16x16x32_bf16 v[188:191], v[84:87], v[20:23], v[190:193]
	v_exp_f32_e32 v136, v138
	v_exp_f32_e32 v134, v139
	v_mfma_f32_16x16x32_bf16 v[88:91], v[76:79], v[24:27], v[60:63]
	v_exp_f32_e32 v139, v124
	v_mfma_f32_16x16x32_bf16 v[60:63], v[204:207], v[8:11], v[72:75]
	v_exp_f32_e32 v138, v128
	s_waitcnt lgkmcnt(0)
	v_mfma_f32_16x16x32_bf16 v[72:75], v[220:223], v[24:27], v[188:191]
	v_exp_f32_e32 v147, v125
	ds_read_b128 v[190:193], v200 offset:32768
	v_mfma_f32_16x16x32_bf16 v[208:211], v[84:87], v[4:7], v[208:211]
	v_exp_f32_e32 v146, v129
	v_mfma_f32_16x16x32_bf16 v[84:87], v[76:79], v[8:11], v[68:71]
	v_exp_f32_e32 v125, v126
	v_mfma_f32_16x16x32_bf16 v[76:79], v[212:215], v[8:11], v[80:83]
	v_exp_f32_e32 v124, v130
	v_mfma_f32_16x16x32_bf16 v[80:83], v[212:215], v[24:27], v[64:67]
	v_exp_f32_e32 v126, v131
	v_mfma_f32_16x16x32_bf16 v[68:71], v[204:207], v[24:27], v[216:219]
	ds_read_b128 v[212:215], v200 offset:34816
	s_nop 1
	ds_read_b128 v[216:219], v200 offset:33792
	v_cvt_pk_bf16_f32 v204, v249, v149
	v_cvt_pk_bf16_f32 v205, v153, v151
	v_mfma_f32_16x16x32_bf16 v[64:67], v[220:223], v[8:11], v[208:211]
	v_cvt_pk_bf16_f32 v206, v251, v155
	v_cvt_pk_bf16_f32 v207, v145, v143
	v_cvt_pk_bf16_f32 v208, v248, v148
	v_cvt_pk_bf16_f32 v209, v152, v150
	v_cvt_pk_bf16_f32 v210, v250, v154
	v_cvt_pk_bf16_f32 v211, v144, v142
	s_waitcnt lgkmcnt(2)
	v_mfma_f32_16x16x32_bf16 v[120:123], v[190:193], v[204:207], v[120:123]
	v_mfma_f32_16x16x32_bf16 v[116:119], v[190:193], v[208:211], v[116:119]
	ds_read_b128 v[190:193], v200 offset:36864
	ds_read_b128 v[220:223], v200 offset:35840
	s_waitcnt lgkmcnt(3)
	v_mfma_f32_16x16x32_bf16 v[112:115], v[212:215], v[204:207], v[112:115]
	v_mfma_f32_16x16x32_bf16 v[108:111], v[212:215], v[208:211], v[108:111]
	ds_read_b128 v[212:215], v200 offset:38912
	ds_read_b128 v[224:227], v200 offset:37888
	ds_read_b128 v[232:235], v200 offset:39936
	s_waitcnt lgkmcnt(4)
	v_mfma_f32_16x16x32_bf16 v[228:231], v[190:193], v[204:207], v[104:107]
	v_mfma_f32_16x16x32_bf16 v[190:193], v[190:193], v[208:211], v[100:103]
	s_waitcnt lgkmcnt(2)
	v_mfma_f32_16x16x32_bf16 v[92:95], v[212:215], v[204:207], v[92:95]
	v_cvt_pk_bf16_f32 v204, v141, v133
	v_cvt_pk_bf16_f32 v205, v137, v135
	v_cvt_pk_bf16_f32 v206, v139, v147
	v_mfma_f32_16x16x32_bf16 v[128:131], v[212:215], v[208:211], v[96:99]
	v_cvt_pk_bf16_f32 v207, v125, v127
	v_cvt_pk_bf16_f32 v208, v140, v132
	v_cvt_pk_bf16_f32 v209, v136, v134
	v_cvt_pk_bf16_f32 v210, v138, v146
	v_cvt_pk_bf16_f32 v211, v124, v126
	v_mfma_f32_16x16x32_bf16 v[120:123], v[216:219], v[204:207], v[120:123]
	s_nop 0
	v_mfma_f32_16x16x32_bf16 v[104:107], v[216:219], v[208:211], v[116:119]
	v_max3_f32 v246, v88, v89, v90
	v_max3_f32 v247, v84, v85, v86
	v_mfma_f32_16x16x32_bf16 v[116:119], v[220:223], v[204:207], v[112:115]
	v_max3_f32 v246, v246, v91, v80
	v_max3_f32 v247, v247, v87, v76
	v_mfma_f32_16x16x32_bf16 v[100:103], v[220:223], v[208:211], v[108:111]
	v_max3_f32 v246, v246, v81, v82
	v_max3_f32 v247, v247, v77, v78
	s_waitcnt lgkmcnt(1)
	v_mfma_f32_16x16x32_bf16 v[112:115], v[224:227], v[204:207], v[228:231]
	v_max3_f32 v246, v246, v83, v68
	v_max3_f32 v247, v247, v79, v60
	v_mfma_f32_16x16x32_bf16 v[96:99], v[224:227], v[208:211], v[190:193]
	v_max3_f32 v246, v246, v69, v70
	v_max3_f32 v247, v247, v61, v62
	s_waitcnt lgkmcnt(0)
	v_mfma_f32_16x16x32_bf16 v[108:111], v[232:235], v[204:207], v[92:95]
	v_max3_f32 v246, v246, v71, v72
	v_max3_f32 v247, v247, v63, v64
	v_mfma_f32_16x16x32_bf16 v[92:95], v[232:235], v[208:211], v[128:131]
	v_max3_f32 v246, v246, v73, v74
	v_max3_f32 v247, v247, v65, v66
	s_waitcnt vmcnt(0)
	ds_write_b128 v197, v[52:55] offset:40960
	s_and_saveexec_b64 s[16:17], s[10:11]
	ds_write_b128 v199, v[28:31] offset:40960
	s_or_b64 exec, exec, s[16:17]
